# combine phase: all 8 loads of a token row issued at the top of the row (4x the loads in flight per wave)
# speedup vs baseline: 1.0053x; 1.0017x over previous
.LBB0_568:
	s_nop 0
	v_lshl_add_u64 v[16:17], s[4:5], 0, v[0:1]
	v_add_co_u32_e32 v14, vcc, 0x24800000, v16
	v_lshl_add_u64 v[12:13], s[8:9], 0, v[0:1]
	s_nop 0
	v_addc_co_u32_e32 v15, vcc, 0, v17, vcc
	v_add_co_u32_e32 v16, vcc, 0x2c800000, v16
	global_load_dwordx4 v[20:23], v[14:15], off
	s_nop 0
	v_addc_co_u32_e32 v17, vcc, 0, v17, vcc
	global_load_dwordx4 v[24:27], v[16:17], off
	global_load_dwordx4 v[36:39], v[14:15], off offset:1024
	global_load_dwordx4 v[40:43], v[16:17], off offset:1024
	global_load_dwordx4 v[44:47], v[14:15], off offset:2048
	global_load_dwordx4 v[48:51], v[16:17], off offset:2048
	global_load_dwordx4 v[52:55], v[14:15], off offset:3072
	global_load_dwordx4 v[56:59], v[16:17], off offset:3072
	v_add_co_u32_e64 v12, s[0:1], s12, v12
	s_add_i32 s10, s10, s22
	s_nop 0
	v_addc_co_u32_e64 v13, s[0:1], 0, v13, s[0:1]
	s_add_u32 s4, s4, s6
	s_addc_u32 s5, s5, s7
	s_add_u32 s8, s8, s6
	s_addc_u32 s9, s9, s7
	s_cmp_lt_i32 s10, 0x8000
	s_waitcnt vmcnt(7)
	v_lshlrev_b32_e32 v29, 16, v21
	v_lshlrev_b32_e32 v28, 16, v20
	v_and_b32_e32 v21, 0xffff0000, v21
	s_waitcnt vmcnt(6)
	v_lshlrev_b32_e32 v33, 16, v25
	v_lshlrev_b32_e32 v32, 16, v24
	v_and_b32_e32 v20, 0xffff0000, v20
	v_lshlrev_b32_e32 v31, 16, v23
	v_lshlrev_b32_e32 v30, 16, v22
	v_and_b32_e32 v23, 0xffff0000, v23
	v_and_b32_e32 v22, 0xffff0000, v22
	v_and_b32_e32 v25, 0xffff0000, v25
	v_and_b32_e32 v24, 0xffff0000, v24
	v_lshlrev_b32_e32 v35, 16, v27
	v_lshlrev_b32_e32 v34, 16, v26
	v_and_b32_e32 v27, 0xffff0000, v27
	v_and_b32_e32 v26, 0xffff0000, v26
	v_pk_fma_f32 v[28:29], v[2:3], v[32:33], v[28:29] neg_lo:[1,0,0] neg_hi:[1,0,0]
	v_pk_fma_f32 v[20:21], v[2:3], v[24:25], v[20:21] neg_lo:[1,0,0] neg_hi:[1,0,0]
	v_pk_fma_f32 v[24:25], v[2:3], v[34:35], v[30:31] neg_lo:[1,0,0] neg_hi:[1,0,0]
	v_pk_fma_f32 v[22:23], v[2:3], v[26:27], v[22:23] neg_lo:[1,0,0] neg_hi:[1,0,0]
	v_pk_mul_f32 v[26:27], v[28:29], v[28:29]
	v_pk_mul_f32 v[30:31], v[24:25], v[24:25]
	v_pk_fma_f32 v[26:27], v[20:21], v[20:21], v[26:27]
	v_pk_fma_f32 v[30:31], v[22:23], v[22:23], v[30:31]
	v_add_f32_e32 v26, v26, v27
	v_add_f32_e32 v26, v30, v26
	v_add_f32_e32 v26, v31, v26
	ds_bpermute_b32 v27, v178, v26
	s_waitcnt lgkmcnt(0)
	v_add_f32_e32 v26, v26, v27
	ds_bpermute_b32 v27, v156, v26
	s_waitcnt lgkmcnt(0)
	v_add_f32_e32 v26, v26, v27
	ds_bpermute_b32 v27, v157, v26
	s_waitcnt lgkmcnt(0)
	v_add_f32_e32 v26, v26, v27
	ds_bpermute_b32 v27, v158, v26
	s_waitcnt lgkmcnt(0)
	v_add_f32_e32 v26, v26, v27
	ds_bpermute_b32 v27, v176, v26
	s_waitcnt lgkmcnt(0)
	v_add_f32_e32 v26, v26, v27
	v_fmamk_f32 v26, v26, 0x3b800000, v18
	v_mul_f32_e32 v27, 0x4f800000, v26
	v_cmp_gt_f32_e32 vcc, s3, v26
	s_nop 1
	v_cndmask_b32_e32 v26, v26, v27, vcc
	v_sqrt_f32_e32 v27, v26
	s_nop 0
	v_add_u32_e32 v30, -1, v27
	v_add_u32_e32 v31, 1, v27
	v_fma_f32 v32, -v30, v27, v26
	v_fma_f32 v33, -v31, v27, v26
	v_cmp_ge_f32_e64 s[0:1], 0, v32
	s_nop 1
	v_cndmask_b32_e64 v27, v27, v30, s[0:1]
	v_cmp_lt_f32_e64 s[0:1], 0, v33
	s_nop 1
	v_cndmask_b32_e64 v27, v27, v31, s[0:1]
	v_mul_f32_e32 v30, 0x37800000, v27
	v_cndmask_b32_e32 v27, v27, v30, vcc
	v_cmp_class_f32_e32 vcc, v26, v19
	s_nop 1
	v_cndmask_b32_e32 v26, v27, v26, vcc
	v_div_scale_f32 v27, s[0:1], v26, v26, 1.0
	v_rcp_f32_e32 v31, v27
	v_div_scale_f32 v30, vcc, 1.0, v26, 1.0
	v_fma_f32 v32, -v27, v31, 1.0
	v_fmac_f32_e32 v31, v32, v31
	v_mul_f32_e32 v32, v30, v31
	v_fma_f32 v33, -v27, v32, v30
	v_fmac_f32_e32 v32, v33, v31
	v_fma_f32 v27, -v27, v32, v30
	v_div_fmas_f32 v27, v27, v31, v32
	v_div_fixup_f32 v26, v27, v26, 1.0
	v_pk_mul_f32 v[28:29], v[28:29], v[26:27] op_sel_hi:[1,0]
	v_pk_mul_f32 v[24:25], v[24:25], v[26:27] op_sel_hi:[1,0]
	v_pk_mul_f32 v[20:21], v[20:21], v[26:27] op_sel_hi:[1,0]
	v_pk_mul_f32 v[22:23], v[22:23], v[26:27] op_sel_hi:[1,0]
	v_pk_mul_f32 v[26:27], v[4:5], v[28:29]
	v_pk_mul_f32 v[24:25], v[8:9], v[24:25]
	v_pk_mul_f32 v[20:21], v[6:7], v[20:21]
	v_pk_mul_f32 v[22:23], v[10:11], v[22:23]
	v_bfe_u32 v32, v26, 16, 1
	v_bfe_u32 v33, v27, 16, 1
	v_bfe_u32 v34, v24, 16, 1
	v_bfe_u32 v35, v25, 16, 1
	v_bfe_u32 v28, v23, 16, 1
	v_bfe_u32 v29, v22, 16, 1
	v_bfe_u32 v30, v21, 16, 1
	v_bfe_u32 v31, v20, 16, 1
	v_add3_u32 v25, v25, v35, s11
	v_add3_u32 v24, v24, v34, s11
	v_add3_u32 v27, v27, v33, s11
	v_add3_u32 v26, v26, v32, s11
	v_add3_u32 v20, v20, v31, s11
	v_add3_u32 v21, v21, v30, s11
	v_add3_u32 v22, v22, v29, s11
	v_add3_u32 v23, v23, v28, s11
	v_lshrrev_b32_e32 v26, 16, v26
	v_lshrrev_b32_e32 v27, 16, v27
	v_lshrrev_b32_e32 v24, 16, v24
	v_lshrrev_b32_e32 v25, 16, v25
	v_and_or_b32 v23, v23, s2, v25
	v_and_or_b32 v22, v22, s2, v24
	v_and_or_b32 v21, v21, s2, v27
	v_and_or_b32 v20, v20, s2, v26
	global_store_dwordx4 v[12:13], v[20:23], off
	s_waitcnt vmcnt(5)
	s_nop 1
	v_mov_b32_e32 v20, v36
	v_mov_b32_e32 v21, v37
	v_mov_b32_e32 v22, v38
	v_mov_b32_e32 v23, v39
	v_mov_b32_e32 v24, v40
	v_mov_b32_e32 v25, v41
	v_mov_b32_e32 v26, v42
	v_mov_b32_e32 v27, v43
	v_lshlrev_b32_e32 v29, 16, v21
	v_lshlrev_b32_e32 v28, 16, v20
	v_lshlrev_b32_e32 v31, 16, v25
	v_lshlrev_b32_e32 v30, 16, v24
	v_and_b32_e32 v21, 0xffff0000, v21
	v_and_b32_e32 v20, 0xffff0000, v20
	v_and_b32_e32 v25, 0xffff0000, v25
	v_and_b32_e32 v24, 0xffff0000, v24
	v_lshlrev_b32_e32 v33, 16, v23
	v_lshlrev_b32_e32 v32, 16, v22
	v_lshlrev_b32_e32 v35, 16, v27
	v_lshlrev_b32_e32 v34, 16, v26
	v_and_b32_e32 v23, 0xffff0000, v23
	v_and_b32_e32 v22, 0xffff0000, v22
	v_and_b32_e32 v27, 0xffff0000, v27
	v_and_b32_e32 v26, 0xffff0000, v26
	v_pk_fma_f32 v[28:29], v[2:3], v[30:31], v[28:29] neg_lo:[1,0,0] neg_hi:[1,0,0]
	v_pk_fma_f32 v[20:21], v[2:3], v[24:25], v[20:21] neg_lo:[1,0,0] neg_hi:[1,0,0]
	v_pk_fma_f32 v[24:25], v[2:3], v[34:35], v[32:33] neg_lo:[1,0,0] neg_hi:[1,0,0]
	v_pk_fma_f32 v[22:23], v[2:3], v[26:27], v[22:23] neg_lo:[1,0,0] neg_hi:[1,0,0]
	v_pk_mul_f32 v[26:27], v[28:29], v[28:29]
	v_pk_mul_f32 v[30:31], v[24:25], v[24:25]
	v_pk_fma_f32 v[26:27], v[20:21], v[20:21], v[26:27]
	v_pk_fma_f32 v[30:31], v[22:23], v[22:23], v[30:31]
	v_add_f32_e32 v26, v26, v27
	v_add_f32_e32 v26, v30, v26
	v_add_f32_e32 v26, v31, v26
	ds_bpermute_b32 v27, v178, v26
	s_waitcnt lgkmcnt(0)
	v_add_f32_e32 v26, v26, v27
	ds_bpermute_b32 v27, v156, v26
	s_waitcnt lgkmcnt(0)
	v_add_f32_e32 v26, v26, v27
	ds_bpermute_b32 v27, v157, v26
	s_waitcnt lgkmcnt(0)
	v_add_f32_e32 v26, v26, v27
	ds_bpermute_b32 v27, v158, v26
	s_waitcnt lgkmcnt(0)
	v_add_f32_e32 v26, v26, v27
	ds_bpermute_b32 v27, v176, v26
	s_waitcnt lgkmcnt(0)
	v_add_f32_e32 v26, v26, v27
	v_fmamk_f32 v26, v26, 0x3b800000, v18
	v_mul_f32_e32 v27, 0x4f800000, v26
	v_cmp_gt_f32_e32 vcc, s3, v26
	s_nop 1
	v_cndmask_b32_e32 v26, v26, v27, vcc
	v_sqrt_f32_e32 v27, v26
	s_nop 0
	v_add_u32_e32 v30, -1, v27
	v_add_u32_e32 v31, 1, v27
	v_fma_f32 v32, -v30, v27, v26
	v_fma_f32 v33, -v31, v27, v26
	v_cmp_ge_f32_e64 s[0:1], 0, v32
	s_nop 1
	v_cndmask_b32_e64 v27, v27, v30, s[0:1]
	v_cmp_lt_f32_e64 s[0:1], 0, v33
	s_nop 1
	v_cndmask_b32_e64 v27, v27, v31, s[0:1]
	v_mul_f32_e32 v30, 0x37800000, v27
	v_cndmask_b32_e32 v27, v27, v30, vcc
	v_cmp_class_f32_e32 vcc, v26, v19
	s_nop 1
	v_cndmask_b32_e32 v26, v27, v26, vcc
	v_div_scale_f32 v27, s[0:1], v26, v26, 1.0
	v_rcp_f32_e32 v31, v27
	v_div_scale_f32 v30, vcc, 1.0, v26, 1.0
	v_fma_f32 v32, -v27, v31, 1.0
	v_fmac_f32_e32 v31, v32, v31
	v_mul_f32_e32 v32, v30, v31
	v_fma_f32 v33, -v27, v32, v30
	v_fmac_f32_e32 v32, v33, v31
	v_fma_f32 v27, -v27, v32, v30
	v_div_fmas_f32 v27, v27, v31, v32
	v_div_fixup_f32 v26, v27, v26, 1.0
	v_pk_mul_f32 v[28:29], v[28:29], v[26:27] op_sel_hi:[1,0]
	v_pk_mul_f32 v[24:25], v[24:25], v[26:27] op_sel_hi:[1,0]
	v_pk_mul_f32 v[20:21], v[20:21], v[26:27] op_sel_hi:[1,0]
	v_pk_mul_f32 v[22:23], v[22:23], v[26:27] op_sel_hi:[1,0]
	v_pk_mul_f32 v[26:27], v[4:5], v[28:29]
	v_pk_mul_f32 v[24:25], v[8:9], v[24:25]
	v_pk_mul_f32 v[20:21], v[6:7], v[20:21]
	v_pk_mul_f32 v[22:23], v[10:11], v[22:23]
	v_bfe_u32 v32, v26, 16, 1
	v_bfe_u32 v33, v27, 16, 1
	v_bfe_u32 v34, v24, 16, 1
	v_bfe_u32 v35, v25, 16, 1
	v_bfe_u32 v28, v23, 16, 1
	v_bfe_u32 v29, v22, 16, 1
	v_bfe_u32 v30, v21, 16, 1
	v_bfe_u32 v31, v20, 16, 1
	v_add3_u32 v25, v25, v35, s11
	v_add3_u32 v24, v24, v34, s11
	v_add3_u32 v27, v27, v33, s11
	v_add3_u32 v26, v26, v32, s11
	v_add3_u32 v20, v20, v31, s11
	v_add3_u32 v21, v21, v30, s11
	v_add3_u32 v22, v22, v29, s11
	v_add3_u32 v23, v23, v28, s11
	v_lshrrev_b32_e32 v26, 16, v26
	v_lshrrev_b32_e32 v27, 16, v27
	v_lshrrev_b32_e32 v24, 16, v24
	v_lshrrev_b32_e32 v25, 16, v25
	v_and_or_b32 v23, v23, s2, v25
	v_and_or_b32 v22, v22, s2, v24
	v_and_or_b32 v21, v21, s2, v27
	v_and_or_b32 v20, v20, s2, v26
	global_store_dwordx4 v[12:13], v[20:23], off offset:1024
	s_waitcnt vmcnt(4)
	s_nop 1
	v_mov_b32_e32 v20, v44
	v_mov_b32_e32 v21, v45
	v_mov_b32_e32 v22, v46
	v_mov_b32_e32 v23, v47
	v_mov_b32_e32 v24, v48
	v_mov_b32_e32 v25, v49
	v_mov_b32_e32 v26, v50
	v_mov_b32_e32 v27, v51
	v_lshlrev_b32_e32 v29, 16, v21
	v_lshlrev_b32_e32 v28, 16, v20
	v_lshlrev_b32_e32 v31, 16, v25
	v_lshlrev_b32_e32 v30, 16, v24
	v_and_b32_e32 v21, 0xffff0000, v21
	v_and_b32_e32 v20, 0xffff0000, v20
	v_and_b32_e32 v25, 0xffff0000, v25
	v_and_b32_e32 v24, 0xffff0000, v24
	v_lshlrev_b32_e32 v33, 16, v23
	v_lshlrev_b32_e32 v32, 16, v22
	v_lshlrev_b32_e32 v35, 16, v27
	v_lshlrev_b32_e32 v34, 16, v26
	v_and_b32_e32 v23, 0xffff0000, v23
	v_and_b32_e32 v22, 0xffff0000, v22
	v_and_b32_e32 v27, 0xffff0000, v27
	v_and_b32_e32 v26, 0xffff0000, v26
	v_pk_fma_f32 v[28:29], v[2:3], v[30:31], v[28:29] neg_lo:[1,0,0] neg_hi:[1,0,0]
	v_pk_fma_f32 v[20:21], v[2:3], v[24:25], v[20:21] neg_lo:[1,0,0] neg_hi:[1,0,0]
	v_pk_fma_f32 v[24:25], v[2:3], v[34:35], v[32:33] neg_lo:[1,0,0] neg_hi:[1,0,0]
	v_pk_fma_f32 v[22:23], v[2:3], v[26:27], v[22:23] neg_lo:[1,0,0] neg_hi:[1,0,0]
	v_pk_mul_f32 v[26:27], v[28:29], v[28:29]
	v_pk_mul_f32 v[30:31], v[24:25], v[24:25]
	v_pk_fma_f32 v[26:27], v[20:21], v[20:21], v[26:27]
	v_pk_fma_f32 v[30:31], v[22:23], v[22:23], v[30:31]
	v_add_f32_e32 v26, v26, v27
	v_add_f32_e32 v26, v30, v26
	v_add_f32_e32 v26, v31, v26
	ds_bpermute_b32 v27, v178, v26
	s_waitcnt lgkmcnt(0)
	v_add_f32_e32 v26, v26, v27
	ds_bpermute_b32 v27, v156, v26
	s_waitcnt lgkmcnt(0)
	v_add_f32_e32 v26, v26, v27
	ds_bpermute_b32 v27, v157, v26
	s_waitcnt lgkmcnt(0)
	v_add_f32_e32 v26, v26, v27
	ds_bpermute_b32 v27, v158, v26
	s_waitcnt lgkmcnt(0)
	v_add_f32_e32 v26, v26, v27
	ds_bpermute_b32 v27, v176, v26
	s_waitcnt lgkmcnt(0)
	v_add_f32_e32 v26, v26, v27
	v_fmamk_f32 v26, v26, 0x3b800000, v18
	v_mul_f32_e32 v27, 0x4f800000, v26
	v_cmp_gt_f32_e32 vcc, s3, v26
	s_nop 1
	v_cndmask_b32_e32 v26, v26, v27, vcc
	v_sqrt_f32_e32 v27, v26
	s_nop 0
	v_add_u32_e32 v30, -1, v27
	v_add_u32_e32 v31, 1, v27
	v_fma_f32 v32, -v30, v27, v26
	v_fma_f32 v33, -v31, v27, v26
	v_cmp_ge_f32_e64 s[0:1], 0, v32
	s_nop 1
	v_cndmask_b32_e64 v27, v27, v30, s[0:1]
	v_cmp_lt_f32_e64 s[0:1], 0, v33
	s_nop 1
	v_cndmask_b32_e64 v27, v27, v31, s[0:1]
	v_mul_f32_e32 v30, 0x37800000, v27
	v_cndmask_b32_e32 v27, v27, v30, vcc
	v_cmp_class_f32_e32 vcc, v26, v19
	s_nop 1
	v_cndmask_b32_e32 v26, v27, v26, vcc
	v_div_scale_f32 v27, s[0:1], v26, v26, 1.0
	v_rcp_f32_e32 v31, v27
	v_div_scale_f32 v30, vcc, 1.0, v26, 1.0
	v_fma_f32 v32, -v27, v31, 1.0
	v_fmac_f32_e32 v31, v32, v31
	v_mul_f32_e32 v32, v30, v31
	v_fma_f32 v33, -v27, v32, v30
	v_fmac_f32_e32 v32, v33, v31
	v_fma_f32 v27, -v27, v32, v30
	v_div_fmas_f32 v27, v27, v31, v32
	v_div_fixup_f32 v26, v27, v26, 1.0
	v_pk_mul_f32 v[28:29], v[28:29], v[26:27] op_sel_hi:[1,0]
	v_pk_mul_f32 v[24:25], v[24:25], v[26:27] op_sel_hi:[1,0]
	v_pk_mul_f32 v[20:21], v[20:21], v[26:27] op_sel_hi:[1,0]
	v_pk_mul_f32 v[22:23], v[22:23], v[26:27] op_sel_hi:[1,0]
	v_pk_mul_f32 v[26:27], v[4:5], v[28:29]
	v_pk_mul_f32 v[24:25], v[8:9], v[24:25]
	v_pk_mul_f32 v[20:21], v[6:7], v[20:21]
	v_pk_mul_f32 v[22:23], v[10:11], v[22:23]
	v_bfe_u32 v32, v26, 16, 1
	v_bfe_u32 v33, v27, 16, 1
	v_bfe_u32 v34, v24, 16, 1
	v_bfe_u32 v35, v25, 16, 1
	v_bfe_u32 v28, v23, 16, 1
	v_bfe_u32 v29, v22, 16, 1
	v_bfe_u32 v30, v21, 16, 1
	v_bfe_u32 v31, v20, 16, 1
	v_add3_u32 v25, v25, v35, s11
	v_add3_u32 v24, v24, v34, s11
	v_add3_u32 v27, v27, v33, s11
	v_add3_u32 v26, v26, v32, s11
	v_add3_u32 v20, v20, v31, s11
	v_add3_u32 v21, v21, v30, s11
	v_add3_u32 v22, v22, v29, s11
	v_add3_u32 v23, v23, v28, s11
	v_lshrrev_b32_e32 v26, 16, v26
	v_lshrrev_b32_e32 v27, 16, v27
	v_lshrrev_b32_e32 v24, 16, v24
	v_lshrrev_b32_e32 v25, 16, v25
	v_and_or_b32 v23, v23, s2, v25
	v_and_or_b32 v22, v22, s2, v24
	v_and_or_b32 v21, v21, s2, v27
	v_and_or_b32 v20, v20, s2, v26
	global_store_dwordx4 v[12:13], v[20:23], off offset:2048
	s_waitcnt vmcnt(3)
	s_nop 1
	v_mov_b32_e32 v20, v52
	v_mov_b32_e32 v21, v53
	v_mov_b32_e32 v22, v54
	v_mov_b32_e32 v23, v55
	v_mov_b32_e32 v14, v56
	v_mov_b32_e32 v15, v57
	v_mov_b32_e32 v16, v58
	v_mov_b32_e32 v17, v59
	v_lshlrev_b32_e32 v25, 16, v21
	v_lshlrev_b32_e32 v24, 16, v20
	v_lshlrev_b32_e32 v27, 16, v15
	v_lshlrev_b32_e32 v26, 16, v14
	v_and_b32_e32 v21, 0xffff0000, v21
	v_and_b32_e32 v20, 0xffff0000, v20
	v_and_b32_e32 v15, 0xffff0000, v15
	v_and_b32_e32 v14, 0xffff0000, v14
	v_lshlrev_b32_e32 v29, 16, v23
	v_lshlrev_b32_e32 v28, 16, v22
	v_lshlrev_b32_e32 v31, 16, v17
	v_lshlrev_b32_e32 v30, 16, v16
	v_and_b32_e32 v23, 0xffff0000, v23
	v_and_b32_e32 v22, 0xffff0000, v22
	v_and_b32_e32 v17, 0xffff0000, v17
	v_and_b32_e32 v16, 0xffff0000, v16
	v_pk_fma_f32 v[24:25], v[2:3], v[26:27], v[24:25] neg_lo:[1,0,0] neg_hi:[1,0,0]
	v_pk_fma_f32 v[14:15], v[2:3], v[14:15], v[20:21] neg_lo:[1,0,0] neg_hi:[1,0,0]
	v_pk_fma_f32 v[20:21], v[2:3], v[30:31], v[28:29] neg_lo:[1,0,0] neg_hi:[1,0,0]
	v_pk_fma_f32 v[16:17], v[2:3], v[16:17], v[22:23] neg_lo:[1,0,0] neg_hi:[1,0,0]
	v_pk_mul_f32 v[22:23], v[24:25], v[24:25]
	v_pk_mul_f32 v[26:27], v[20:21], v[20:21]
	v_pk_fma_f32 v[22:23], v[14:15], v[14:15], v[22:23]
	v_pk_fma_f32 v[26:27], v[16:17], v[16:17], v[26:27]
	v_add_f32_e32 v22, v22, v23
	v_add_f32_e32 v22, v26, v22
	v_add_f32_e32 v22, v27, v22
	ds_bpermute_b32 v23, v178, v22
	s_waitcnt lgkmcnt(0)
	v_add_f32_e32 v22, v22, v23
	ds_bpermute_b32 v23, v156, v22
	s_waitcnt lgkmcnt(0)
	v_add_f32_e32 v22, v22, v23
	ds_bpermute_b32 v23, v157, v22
	s_waitcnt lgkmcnt(0)
	v_add_f32_e32 v22, v22, v23
	ds_bpermute_b32 v23, v158, v22
	s_waitcnt lgkmcnt(0)
	v_add_f32_e32 v22, v22, v23
	ds_bpermute_b32 v23, v176, v22
	s_waitcnt lgkmcnt(0)
	v_add_f32_e32 v22, v22, v23
	v_fmamk_f32 v22, v22, 0x3b800000, v18
	v_mul_f32_e32 v23, 0x4f800000, v22
	v_cmp_gt_f32_e32 vcc, s3, v22
	s_nop 1
	v_cndmask_b32_e32 v22, v22, v23, vcc
	v_sqrt_f32_e32 v23, v22
	s_nop 0
	v_add_u32_e32 v26, -1, v23
	v_add_u32_e32 v27, 1, v23
	v_fma_f32 v28, -v26, v23, v22
	v_fma_f32 v29, -v27, v23, v22
	v_cmp_ge_f32_e64 s[0:1], 0, v28
	s_nop 1
	v_cndmask_b32_e64 v23, v23, v26, s[0:1]
	v_cmp_lt_f32_e64 s[0:1], 0, v29
	s_nop 1
	v_cndmask_b32_e64 v23, v23, v27, s[0:1]
	v_mul_f32_e32 v26, 0x37800000, v23
	v_cndmask_b32_e32 v23, v23, v26, vcc
	v_cmp_class_f32_e32 vcc, v22, v19
	s_nop 1
	v_cndmask_b32_e32 v22, v23, v22, vcc
	v_div_scale_f32 v23, s[0:1], v22, v22, 1.0
	v_rcp_f32_e32 v27, v23
	v_div_scale_f32 v26, vcc, 1.0, v22, 1.0
	v_fma_f32 v28, -v23, v27, 1.0
	v_fmac_f32_e32 v27, v28, v27
	v_mul_f32_e32 v28, v26, v27
	v_fma_f32 v29, -v23, v28, v26
	v_fmac_f32_e32 v28, v29, v27
	v_fma_f32 v23, -v23, v28, v26
	v_div_fmas_f32 v23, v23, v27, v28
	v_div_fixup_f32 v22, v23, v22, 1.0
	v_pk_mul_f32 v[24:25], v[24:25], v[22:23] op_sel_hi:[1,0]
	v_pk_mul_f32 v[20:21], v[20:21], v[22:23] op_sel_hi:[1,0]
	v_pk_mul_f32 v[14:15], v[14:15], v[22:23] op_sel_hi:[1,0]
	v_pk_mul_f32 v[16:17], v[16:17], v[22:23] op_sel_hi:[1,0]
	v_pk_mul_f32 v[22:23], v[4:5], v[24:25]
	v_pk_mul_f32 v[20:21], v[8:9], v[20:21]
	v_pk_mul_f32 v[14:15], v[6:7], v[14:15]
	v_pk_mul_f32 v[16:17], v[10:11], v[16:17]
	v_bfe_u32 v28, v22, 16, 1
	v_bfe_u32 v29, v23, 16, 1
	v_bfe_u32 v30, v20, 16, 1
	v_bfe_u32 v31, v21, 16, 1
	v_bfe_u32 v24, v17, 16, 1
	v_bfe_u32 v25, v16, 16, 1
	v_bfe_u32 v26, v15, 16, 1
	v_bfe_u32 v27, v14, 16, 1
	v_add3_u32 v21, v21, v31, s11
	v_add3_u32 v20, v20, v30, s11
	v_add3_u32 v23, v23, v29, s11
	v_add3_u32 v22, v22, v28, s11
	v_add3_u32 v14, v14, v27, s11
	v_add3_u32 v15, v15, v26, s11
	v_add3_u32 v16, v16, v25, s11
	v_add3_u32 v17, v17, v24, s11
	v_lshrrev_b32_e32 v22, 16, v22
	v_lshrrev_b32_e32 v23, 16, v23
	v_lshrrev_b32_e32 v20, 16, v20
	v_lshrrev_b32_e32 v21, 16, v21
	v_and_or_b32 v17, v17, s2, v21
	v_and_or_b32 v16, v16, s2, v20
	v_and_or_b32 v15, v15, s2, v23
	v_and_or_b32 v14, v14, s2, v22
	global_store_dwordx4 v[12:13], v[14:17], off offset:3072
	s_cbranch_scc1 .LBB0_568
